# grid barrier: arrival sharded over 8 group counters plus a top counter (in unused lower halves of d_out rows 0/1), single polled release word; MLA and dilated bodies deduplicated
# speedup vs baseline: 1.0200x; 1.0190x over previous
_Z14fwd_megakernel6Params:
	s_load_dwordx4 s[68:71], s[0:1], 0x80
	s_load_dwordx16 s[36:51], s[0:1], 0x0
	s_load_dwordx2 s[34:35], s[0:1], 0x90
	s_load_dwordx16 s[16:31], s[0:1], 0x40
	s_mov_b32 s12, s2
	s_waitcnt lgkmcnt(0)
	s_add_u32 s14, s70, 0x1f7a0000
	v_and_b32_e32 v1, 0x3ff, v0
	s_addc_u32 s15, s71, 0
	v_writelane_b32 v244, s16, 0
	s_sub_i32 s2, s35, s34
	s_cmp_lt_i32 s2, 2
	v_writelane_b32 v244, s17, 1
	v_writelane_b32 v244, s18, 2
	v_writelane_b32 v244, s19, 3
	v_writelane_b32 v244, s20, 4
	v_writelane_b32 v244, s21, 5
	v_writelane_b32 v244, s22, 6
	v_writelane_b32 v244, s23, 7
	v_writelane_b32 v244, s24, 8
	v_writelane_b32 v244, s25, 9
	v_writelane_b32 v244, s26, 10
	v_writelane_b32 v244, s27, 11
	v_writelane_b32 v244, s28, 12
	v_writelane_b32 v244, s29, 13
	v_writelane_b32 v244, s30, 14
	v_readfirstlane_b32 s10, v1
	v_writelane_b32 v244, s31, 15
	s_cbranch_scc1 .LBB0_14
	v_or_b32_e32 v2, s12, v1
	v_cmp_eq_u32_e32 vcc, 0, v2
	s_and_saveexec_b64 s[2:3], vcc
	s_cbranch_execz .LBB0_3
	v_mov_b32_e32 v2, 0
	global_store_dword v2, v2, s[14:15] sc1
	global_store_dword v2, v2, s[68:69] sc1
	global_store_dword v2, v2, s[68:69] offset:256 sc1
	global_store_dword v2, v2, s[68:69] offset:512 sc1
	global_store_dword v2, v2, s[68:69] offset:768 sc1
	global_store_dword v2, v2, s[68:69] offset:1024 sc1
	global_store_dword v2, v2, s[68:69] offset:1280 sc1
	global_store_dword v2, v2, s[68:69] offset:1536 sc1
	global_store_dword v2, v2, s[68:69] offset:1792 sc1
	v_mov_b32_e32 v3, 0x1000
	global_store_dword v3, v2, s[68:69] sc1

.LBB0_62:
	s_or_b64 exec, exec, s[2:3]
	s_cmp_lt_i32 s35, 2
	s_cbranch_scc1 .LBB0_71
	s_waitcnt vmcnt(1)
	v_mbcnt_lo_u32_b32 v0, -1, 0
	v_mbcnt_hi_u32_b32 v0, -1, v0
	s_waitcnt vmcnt(0) lgkmcnt(0)
	s_waitcnt lgkmcnt(0)
	v_add_u32_e32 v0, s84, v0
	v_cmp_gt_u32_e32 vcc, 64, v0
	s_barrier
	s_and_saveexec_b64 s[0:1], vcc
	s_cbranch_execz .LBB0_70
	buffer_wbl2 sc1
	s_waitcnt vmcnt(0)
	s_waitcnt vmcnt(0)
	v_cmp_eq_u32_e32 vcc, 0, v0
	s_and_saveexec_b64 s[2:3], vcc
	s_cbranch_execz .LBB0_69
	s_sub_i32 s4, 1, s34
	s_and_b32 s5, s12, 7
	s_sub_i32 s6, s13, s5
	s_add_i32 s6, s6, 7
	s_lshr_b32 s6, s6, 3
	s_mul_i32 s6, s6, s4
	s_lshl_b32 s5, s5, 8
	v_mov_b32_e32 v0, s5
	v_mov_b32_e32 v1, 1
	global_atomic_add v1, v0, v1, s[68:69] sc0
	s_min_u32 s7, s13, 8
	s_mul_i32 s7, s7, s4
	s_waitcnt vmcnt(0)
	v_add_u32_e32 v1, 1, v1
	v_cmp_eq_u32_e32 vcc, s6, v1
	s_cbranch_vccz .Lgb_wait_s0
	v_mov_b32_e32 v0, 0x1000
	v_mov_b32_e32 v1, 1
	global_atomic_add v1, v0, v1, s[68:69] sc0
	s_waitcnt vmcnt(0)
	v_add_u32_e32 v1, 1, v1
	v_cmp_eq_u32_e32 vcc, s7, v1
	s_cbranch_vccz .Lgb_wait_s0
	v_mov_b32_e32 v0, 0
	v_mov_b32_e32 v1, 1
	global_atomic_add v0, v1, s[14:15]
.Lgb_wait_s0:
	v_mov_b32_e32 v0, 0
.Lgb_spin_s0:
	global_load_dword v1, v0, s[14:15] sc1
	s_waitcnt vmcnt(0)
	v_cmp_gt_u32_e32 vcc, s4, v1
	s_cbranch_vccz .Lgb_done_s0
	s_sleep 1
	s_branch .Lgb_spin_s0
.Lgb_done_s0:
.LBB0_69:
	s_or_b64 exec, exec, s[2:3]
	buffer_inv sc1
	s_waitcnt vmcnt(0)

.LBB0_151:
	s_cmp_lt_i32 s35, 3
	s_cbranch_scc1 .LBB0_160
	v_mbcnt_lo_u32_b32 v0, -1, 0
	v_mbcnt_hi_u32_b32 v0, -1, v0
	s_waitcnt vmcnt(0) lgkmcnt(0)
	s_waitcnt vmcnt(0) lgkmcnt(0)
	v_add_u32_e32 v0, s84, v0
	v_cmp_gt_u32_e32 vcc, 64, v0
	s_barrier
	s_and_saveexec_b64 s[0:1], vcc
	s_cbranch_execz .LBB0_159
	buffer_wbl2 sc1
	s_waitcnt vmcnt(0)
	v_cmp_eq_u32_e32 vcc, 0, v0
	s_and_saveexec_b64 s[2:3], vcc
	s_cbranch_execz .LBB0_158
	s_sub_i32 s4, 2, s34
	s_and_b32 s5, s12, 7
	s_sub_i32 s6, s13, s5
	s_add_i32 s6, s6, 7
	s_lshr_b32 s6, s6, 3
	s_mul_i32 s6, s6, s4
	s_lshl_b32 s5, s5, 8
	v_mov_b32_e32 v0, s5
	v_mov_b32_e32 v1, 1
	global_atomic_add v1, v0, v1, s[68:69] sc0
	s_min_u32 s7, s13, 8
	s_mul_i32 s7, s7, s4
	s_waitcnt vmcnt(0)
	v_add_u32_e32 v1, 1, v1
	v_cmp_eq_u32_e32 vcc, s6, v1
	s_cbranch_vccz .Lgb_wait_s1
	v_mov_b32_e32 v0, 0x1000
	v_mov_b32_e32 v1, 1
	global_atomic_add v1, v0, v1, s[68:69] sc0
	s_waitcnt vmcnt(0)
	v_add_u32_e32 v1, 1, v1
	v_cmp_eq_u32_e32 vcc, s7, v1
	s_cbranch_vccz .Lgb_wait_s1
	v_mov_b32_e32 v0, 0
	v_mov_b32_e32 v1, 1
	global_atomic_add v0, v1, s[14:15]

.LBB0_211:
	s_cmp_eq_u32 s100, 1
	s_cbranch_scc1 .Ldil_ret12
	s_cmp_lt_i32 s35, 4
	s_cbranch_scc1 .LBB0_220
	v_mbcnt_lo_u32_b32 v0, -1, 0
	v_mbcnt_hi_u32_b32 v0, -1, v0
	s_waitcnt vmcnt(0) lgkmcnt(0)
	s_waitcnt lgkmcnt(0)
	v_add_u32_e32 v0, s84, v0
	v_cmp_gt_u32_e32 vcc, 64, v0
	s_barrier
	s_and_saveexec_b64 s[0:1], vcc
	s_cbranch_execz .LBB0_219
	buffer_wbl2 sc1
	s_waitcnt vmcnt(0)
	s_waitcnt vmcnt(0)
	v_cmp_eq_u32_e32 vcc, 0, v0
	s_and_saveexec_b64 s[2:3], vcc
	s_cbranch_execz .LBB0_218
	s_sub_i32 s4, 3, s34
	s_and_b32 s5, s12, 7
	s_sub_i32 s6, s13, s5
	s_add_i32 s6, s6, 7
	s_lshr_b32 s6, s6, 3
	s_mul_i32 s6, s6, s4
	s_lshl_b32 s5, s5, 8
	v_mov_b32_e32 v0, s5
	v_mov_b32_e32 v1, 1
	global_atomic_add v1, v0, v1, s[68:69] sc0
	s_min_u32 s7, s13, 8
	s_mul_i32 s7, s7, s4
	s_waitcnt vmcnt(0)
	v_add_u32_e32 v1, 1, v1
	v_cmp_eq_u32_e32 vcc, s6, v1
	s_cbranch_vccz .Lgb_wait_s2
	v_mov_b32_e32 v0, 0x1000
	v_mov_b32_e32 v1, 1
	global_atomic_add v1, v0, v1, s[68:69] sc0
	s_waitcnt vmcnt(0)
	v_add_u32_e32 v1, 1, v1
	v_cmp_eq_u32_e32 vcc, s7, v1
	s_cbranch_vccz .Lgb_wait_s2
	v_mov_b32_e32 v0, 0
	v_mov_b32_e32 v1, 1
	global_atomic_add v0, v1, s[14:15]

.LBB0_245:
	s_cmp_lt_i32 s35, 5
	s_cbranch_scc1 .LBB0_254
	v_mbcnt_lo_u32_b32 v0, -1, 0
	v_mbcnt_hi_u32_b32 v0, -1, v0
	s_waitcnt vmcnt(0) lgkmcnt(0)
	s_waitcnt vmcnt(0) lgkmcnt(0)
	v_add_u32_e32 v0, s84, v0
	v_cmp_gt_u32_e32 vcc, 64, v0
	s_barrier
	s_and_saveexec_b64 s[0:1], vcc
	s_cbranch_execz .LBB0_253
	buffer_wbl2 sc1
	s_waitcnt vmcnt(0)
	v_cmp_eq_u32_e32 vcc, 0, v0
	s_and_saveexec_b64 s[2:3], vcc
	s_cbranch_execz .LBB0_252
	s_sub_i32 s4, 4, s34
	s_and_b32 s5, s12, 7
	s_sub_i32 s6, s13, s5
	s_add_i32 s6, s6, 7
	s_lshr_b32 s6, s6, 3
	s_mul_i32 s6, s6, s4
	s_lshl_b32 s5, s5, 8
	v_mov_b32_e32 v0, s5
	v_mov_b32_e32 v1, 1
	global_atomic_add v1, v0, v1, s[68:69] sc0
	s_min_u32 s7, s13, 8
	s_mul_i32 s7, s7, s4
	s_waitcnt vmcnt(0)
	v_add_u32_e32 v1, 1, v1
	v_cmp_eq_u32_e32 vcc, s6, v1
	s_cbranch_vccz .Lgb_wait_s3
	v_mov_b32_e32 v0, 0x1000
	v_mov_b32_e32 v1, 1
	global_atomic_add v1, v0, v1, s[68:69] sc0
	s_waitcnt vmcnt(0)
	v_add_u32_e32 v1, 1, v1
	v_cmp_eq_u32_e32 vcc, s7, v1
	s_cbranch_vccz .Lgb_wait_s3
	v_mov_b32_e32 v0, 0
	v_mov_b32_e32 v1, 1
	global_atomic_add v0, v1, s[14:15]

.LBB0_289:
	s_cmp_eq_u32 s99, 1
	s_cbranch_scc1 .Lmla_ret14
	s_cmp_lt_i32 s35, 6
	s_cbranch_scc1 .LBB0_298
	v_mbcnt_lo_u32_b32 v0, -1, 0
	v_mbcnt_hi_u32_b32 v0, -1, v0
	s_waitcnt vmcnt(0) lgkmcnt(0)
	s_waitcnt lgkmcnt(0)
	v_add_u32_e32 v0, s84, v0
	v_cmp_gt_u32_e32 vcc, 64, v0
	s_barrier
	s_and_saveexec_b64 s[0:1], vcc
	s_cbranch_execz .LBB0_297
	buffer_wbl2 sc1
	s_waitcnt vmcnt(0)
	s_waitcnt vmcnt(0)
	v_cmp_eq_u32_e32 vcc, 0, v0
	s_and_saveexec_b64 s[2:3], vcc
	s_cbranch_execz .LBB0_296
	s_sub_i32 s4, 5, s34
	s_and_b32 s5, s12, 7
	s_sub_i32 s6, s13, s5
	s_add_i32 s6, s6, 7
	s_lshr_b32 s6, s6, 3
	s_mul_i32 s6, s6, s4
	s_lshl_b32 s5, s5, 8
	v_mov_b32_e32 v0, s5
	v_mov_b32_e32 v1, 1
	global_atomic_add v1, v0, v1, s[68:69] sc0
	s_min_u32 s7, s13, 8
	s_mul_i32 s7, s7, s4
	s_waitcnt vmcnt(0)
	v_add_u32_e32 v1, 1, v1
	v_cmp_eq_u32_e32 vcc, s6, v1
	s_cbranch_vccz .Lgb_wait_s4
	v_mov_b32_e32 v0, 0x1000
	v_mov_b32_e32 v1, 1
	global_atomic_add v1, v0, v1, s[68:69] sc0
	s_waitcnt vmcnt(0)
	v_add_u32_e32 v1, 1, v1
	v_cmp_eq_u32_e32 vcc, s7, v1
	s_cbranch_vccz .Lgb_wait_s4
	v_mov_b32_e32 v0, 0
	v_mov_b32_e32 v1, 1
	global_atomic_add v0, v1, s[14:15]

.LBB0_302:
	s_or_b64 exec, exec, s[2:3]
	s_cmp_lt_u32 s35, 7
	s_cbranch_scc1 .LBB0_311
	v_mbcnt_lo_u32_b32 v0, -1, 0
	v_mbcnt_hi_u32_b32 v0, -1, v0
	s_waitcnt vmcnt(0) lgkmcnt(0)
	s_waitcnt lgkmcnt(0)
	v_add_u32_e32 v0, s84, v0
	v_cmp_gt_u32_e32 vcc, 64, v0
	s_barrier
	s_and_saveexec_b64 s[0:1], vcc
	s_cbranch_execz .LBB0_310
	buffer_wbl2 sc1
	s_waitcnt vmcnt(0)
	s_waitcnt vmcnt(0)
	v_cmp_eq_u32_e32 vcc, 0, v0
	s_and_saveexec_b64 s[2:3], vcc
	s_cbranch_execz .LBB0_309
	s_sub_i32 s4, 6, s34
	s_and_b32 s5, s12, 7
	s_sub_i32 s6, s13, s5
	s_add_i32 s6, s6, 7
	s_lshr_b32 s6, s6, 3
	s_mul_i32 s6, s6, s4
	s_lshl_b32 s5, s5, 8
	v_mov_b32_e32 v0, s5
	v_mov_b32_e32 v1, 1
	global_atomic_add v1, v0, v1, s[68:69] sc0
	s_min_u32 s7, s13, 8
	s_mul_i32 s7, s7, s4
	s_waitcnt vmcnt(0)
	v_add_u32_e32 v1, 1, v1
	v_cmp_eq_u32_e32 vcc, s6, v1
	s_cbranch_vccz .Lgb_wait_s5
	v_mov_b32_e32 v0, 0x1000
	v_mov_b32_e32 v1, 1
	global_atomic_add v1, v0, v1, s[68:69] sc0
	s_waitcnt vmcnt(0)
	v_add_u32_e32 v1, 1, v1
	v_cmp_eq_u32_e32 vcc, s7, v1
	s_cbranch_vccz .Lgb_wait_s5
	v_mov_b32_e32 v0, 0
	v_mov_b32_e32 v1, 1
	global_atomic_add v0, v1, s[14:15]

.LBB0_327:
	s_cmp_lt_i32 s35, 8
	s_cbranch_scc1 .LBB0_336
	v_mbcnt_lo_u32_b32 v0, -1, 0
	v_mbcnt_hi_u32_b32 v0, -1, v0
	s_waitcnt vmcnt(0) lgkmcnt(0)
	s_waitcnt vmcnt(0) lgkmcnt(0)
	v_add_u32_e32 v0, s84, v0
	v_cmp_gt_u32_e32 vcc, 64, v0
	s_barrier
	s_and_saveexec_b64 s[0:1], vcc
	s_cbranch_execz .LBB0_335
	buffer_wbl2 sc1
	s_waitcnt vmcnt(0)
	v_cmp_eq_u32_e32 vcc, 0, v0
	s_and_saveexec_b64 s[2:3], vcc
	s_cbranch_execz .LBB0_334
	s_sub_i32 s4, 7, s34
	s_and_b32 s5, s12, 7
	s_sub_i32 s6, s13, s5
	s_add_i32 s6, s6, 7
	s_lshr_b32 s6, s6, 3
	s_mul_i32 s6, s6, s4
	s_lshl_b32 s5, s5, 8
	v_mov_b32_e32 v0, s5
	v_mov_b32_e32 v1, 1
	global_atomic_add v1, v0, v1, s[68:69] sc0
	s_min_u32 s7, s13, 8
	s_mul_i32 s7, s7, s4
	s_waitcnt vmcnt(0)
	v_add_u32_e32 v1, 1, v1
	v_cmp_eq_u32_e32 vcc, s6, v1
	s_cbranch_vccz .Lgb_wait_s6
	v_mov_b32_e32 v0, 0x1000
	v_mov_b32_e32 v1, 1
	global_atomic_add v1, v0, v1, s[68:69] sc0
	s_waitcnt vmcnt(0)
	v_add_u32_e32 v1, 1, v1
	v_cmp_eq_u32_e32 vcc, s7, v1
	s_cbranch_vccz .Lgb_wait_s6
	v_mov_b32_e32 v0, 0
	v_mov_b32_e32 v1, 1
	global_atomic_add v0, v1, s[14:15]

.LBB0_348:
	s_or_b64 exec, exec, s[2:3]
	s_cmp_lt_i32 s35, 9
	s_cbranch_scc1 .LBB0_357
	v_mbcnt_lo_u32_b32 v0, -1, 0
	v_mbcnt_hi_u32_b32 v0, -1, v0
	s_waitcnt vmcnt(0) lgkmcnt(0)
	s_waitcnt lgkmcnt(0)
	v_add_u32_e32 v0, s84, v0
	v_cmp_gt_u32_e32 vcc, 64, v0
	s_barrier
	s_and_saveexec_b64 s[0:1], vcc
	s_cbranch_execz .LBB0_356
	buffer_wbl2 sc1
	s_waitcnt vmcnt(0)
	s_waitcnt vmcnt(0)
	v_cmp_eq_u32_e32 vcc, 0, v0
	s_and_saveexec_b64 s[2:3], vcc
	s_cbranch_execz .LBB0_355
	s_sub_i32 s4, 8, s34
	s_and_b32 s5, s12, 7
	s_sub_i32 s6, s13, s5
	s_add_i32 s6, s6, 7
	s_lshr_b32 s6, s6, 3
	s_mul_i32 s6, s6, s4
	s_lshl_b32 s5, s5, 8
	v_mov_b32_e32 v0, s5
	v_mov_b32_e32 v1, 1
	global_atomic_add v1, v0, v1, s[68:69] sc0
	s_min_u32 s7, s13, 8
	s_mul_i32 s7, s7, s4
	s_waitcnt vmcnt(0)
	v_add_u32_e32 v1, 1, v1
	v_cmp_eq_u32_e32 vcc, s6, v1
	s_cbranch_vccz .Lgb_wait_s7
	v_mov_b32_e32 v0, 0x1000
	v_mov_b32_e32 v1, 1
	global_atomic_add v1, v0, v1, s[68:69] sc0
	s_waitcnt vmcnt(0)
	v_add_u32_e32 v1, 1, v1
	v_cmp_eq_u32_e32 vcc, s7, v1
	s_cbranch_vccz .Lgb_wait_s7
	v_mov_b32_e32 v0, 0
	v_mov_b32_e32 v1, 1
	global_atomic_add v0, v1, s[14:15]

.LBB0_373:
	s_cmp_lt_i32 s35, 10
	s_cbranch_scc1 .LBB0_382
	v_mbcnt_lo_u32_b32 v0, -1, 0
	v_mbcnt_hi_u32_b32 v0, -1, v0
	s_waitcnt vmcnt(0) lgkmcnt(0)
	s_waitcnt vmcnt(0) lgkmcnt(0)
	v_add_u32_e32 v0, s84, v0
	v_cmp_gt_u32_e32 vcc, 64, v0
	s_barrier
	s_and_saveexec_b64 s[0:1], vcc
	s_cbranch_execz .LBB0_381
	buffer_wbl2 sc1
	s_waitcnt vmcnt(0)
	v_cmp_eq_u32_e32 vcc, 0, v0
	s_and_saveexec_b64 s[2:3], vcc
	s_cbranch_execz .LBB0_380
	s_sub_i32 s4, 9, s34
	s_and_b32 s5, s12, 7
	s_sub_i32 s6, s13, s5
	s_add_i32 s6, s6, 7
	s_lshr_b32 s6, s6, 3
	s_mul_i32 s6, s6, s4
	s_lshl_b32 s5, s5, 8
	v_mov_b32_e32 v0, s5
	v_mov_b32_e32 v1, 1
	global_atomic_add v1, v0, v1, s[68:69] sc0
	s_min_u32 s7, s13, 8
	s_mul_i32 s7, s7, s4
	s_waitcnt vmcnt(0)
	v_add_u32_e32 v1, 1, v1
	v_cmp_eq_u32_e32 vcc, s6, v1
	s_cbranch_vccz .Lgb_wait_s8
	v_mov_b32_e32 v0, 0x1000
	v_mov_b32_e32 v1, 1
	global_atomic_add v1, v0, v1, s[68:69] sc0
	s_waitcnt vmcnt(0)
	v_add_u32_e32 v1, 1, v1
	v_cmp_eq_u32_e32 vcc, s7, v1
	s_cbranch_vccz .Lgb_wait_s8
	v_mov_b32_e32 v0, 0
	v_mov_b32_e32 v1, 1
	global_atomic_add v0, v1, s[14:15]

.LBB0_398:
	s_cmp_lt_i32 s35, 11
	s_cbranch_scc1 .LBB0_407
	v_mbcnt_lo_u32_b32 v0, -1, 0
	v_mbcnt_hi_u32_b32 v0, -1, v0
	s_waitcnt vmcnt(0) lgkmcnt(0)
	s_waitcnt vmcnt(0) lgkmcnt(0)
	v_add_u32_e32 v0, s84, v0
	v_cmp_gt_u32_e32 vcc, 64, v0
	s_barrier
	s_and_saveexec_b64 s[0:1], vcc
	s_cbranch_execz .LBB0_406
	buffer_wbl2 sc1
	s_waitcnt vmcnt(0)
	v_cmp_eq_u32_e32 vcc, 0, v0
	s_and_saveexec_b64 s[2:3], vcc
	s_cbranch_execz .LBB0_405
	s_sub_i32 s4, 10, s34
	s_and_b32 s5, s12, 7
	s_sub_i32 s6, s13, s5
	s_add_i32 s6, s6, 7
	s_lshr_b32 s6, s6, 3
	s_mul_i32 s6, s6, s4
	s_lshl_b32 s5, s5, 8
	v_mov_b32_e32 v0, s5
	v_mov_b32_e32 v1, 1
	global_atomic_add v1, v0, v1, s[68:69] sc0
	s_min_u32 s7, s13, 8
	s_mul_i32 s7, s7, s4
	s_waitcnt vmcnt(0)
	v_add_u32_e32 v1, 1, v1
	v_cmp_eq_u32_e32 vcc, s6, v1
	s_cbranch_vccz .Lgb_wait_s9
	v_mov_b32_e32 v0, 0x1000
	v_mov_b32_e32 v1, 1
	global_atomic_add v1, v0, v1, s[68:69] sc0
	s_waitcnt vmcnt(0)
	v_add_u32_e32 v1, 1, v1
	v_cmp_eq_u32_e32 vcc, s7, v1
	s_cbranch_vccz .Lgb_wait_s9
	v_mov_b32_e32 v0, 0
	v_mov_b32_e32 v1, 1
	global_atomic_add v0, v1, s[14:15]

.LBB0_442:
	s_or_b64 exec, exec, s[0:1]
	s_cmp_lt_i32 s35, 12
	s_cbranch_scc1 .LBB0_451
	v_mbcnt_lo_u32_b32 v0, -1, 0
	v_mbcnt_hi_u32_b32 v0, -1, v0
	s_waitcnt vmcnt(0) lgkmcnt(0)
	s_waitcnt lgkmcnt(0)
	v_add_u32_e32 v0, s84, v0
	v_cmp_gt_u32_e32 vcc, 64, v0
	s_barrier
	s_and_saveexec_b64 s[0:1], vcc
	s_cbranch_execz .LBB0_450
	buffer_wbl2 sc1
	s_waitcnt vmcnt(0)
	s_waitcnt vmcnt(0)
	v_cmp_eq_u32_e32 vcc, 0, v0
	s_and_saveexec_b64 s[2:3], vcc
	s_cbranch_execz .LBB0_449
	s_sub_i32 s4, 11, s34
	s_and_b32 s5, s12, 7
	s_sub_i32 s6, s13, s5
	s_add_i32 s6, s6, 7
	s_lshr_b32 s6, s6, 3
	s_mul_i32 s6, s6, s4
	s_lshl_b32 s5, s5, 8
	v_mov_b32_e32 v0, s5
	v_mov_b32_e32 v1, 1
	global_atomic_add v1, v0, v1, s[68:69] sc0
	s_min_u32 s7, s13, 8
	s_mul_i32 s7, s7, s4
	s_waitcnt vmcnt(0)
	v_add_u32_e32 v1, 1, v1
	v_cmp_eq_u32_e32 vcc, s6, v1
	s_cbranch_vccz .Lgb_wait_s10
	v_mov_b32_e32 v0, 0x1000
	v_mov_b32_e32 v1, 1
	global_atomic_add v1, v0, v1, s[68:69] sc0
	s_waitcnt vmcnt(0)
	v_add_u32_e32 v1, 1, v1
	v_cmp_eq_u32_e32 vcc, s7, v1
	s_cbranch_vccz .Lgb_wait_s10
	v_mov_b32_e32 v0, 0
	v_mov_b32_e32 v1, 1
	global_atomic_add v0, v1, s[14:15]

.LBB0_531:
	s_cmp_lt_i32 s35, 13
	s_cbranch_scc1 .LBB0_540
	v_mbcnt_lo_u32_b32 v0, -1, 0
	v_mbcnt_hi_u32_b32 v0, -1, v0
	s_waitcnt vmcnt(0) lgkmcnt(0)
	s_waitcnt vmcnt(0) lgkmcnt(0)
	v_add_u32_e32 v0, s84, v0
	v_cmp_gt_u32_e32 vcc, 64, v0
	s_barrier
	s_and_saveexec_b64 s[0:1], vcc
	s_cbranch_execz .LBB0_539
	buffer_wbl2 sc1
	s_waitcnt vmcnt(0)
	v_cmp_eq_u32_e32 vcc, 0, v0
	s_and_saveexec_b64 s[2:3], vcc
	s_cbranch_execz .LBB0_538
	s_sub_i32 s4, 12, s34
	s_and_b32 s5, s12, 7
	s_sub_i32 s6, s13, s5
	s_add_i32 s6, s6, 7
	s_lshr_b32 s6, s6, 3
	s_mul_i32 s6, s6, s4
	s_lshl_b32 s5, s5, 8
	v_mov_b32_e32 v0, s5
	v_mov_b32_e32 v1, 1
	global_atomic_add v1, v0, v1, s[68:69] sc0
	s_min_u32 s7, s13, 8
	s_mul_i32 s7, s7, s4
	s_waitcnt vmcnt(0)
	v_add_u32_e32 v1, 1, v1
	v_cmp_eq_u32_e32 vcc, s6, v1
	s_cbranch_vccz .Lgb_wait_s11
	v_mov_b32_e32 v0, 0x1000
	v_mov_b32_e32 v1, 1
	global_atomic_add v1, v0, v1, s[68:69] sc0
	s_waitcnt vmcnt(0)
	v_add_u32_e32 v1, 1, v1
	v_cmp_eq_u32_e32 vcc, s7, v1
	s_cbranch_vccz .Lgb_wait_s11
	v_mov_b32_e32 v0, 0
	v_mov_b32_e32 v1, 1
	global_atomic_add v0, v1, s[14:15]

.Ldil_ret12:
.LBB0_590:
	s_cmp_lt_i32 s35, 14
	s_cbranch_scc1 .LBB0_599
	v_mbcnt_lo_u32_b32 v0, -1, 0
	v_mbcnt_hi_u32_b32 v0, -1, v0
	s_waitcnt vmcnt(0) lgkmcnt(0)
	s_waitcnt lgkmcnt(0)
	v_add_u32_e32 v0, s84, v0
	v_cmp_gt_u32_e32 vcc, 64, v0
	s_barrier
	s_and_saveexec_b64 s[0:1], vcc
	s_cbranch_execz .LBB0_598
	buffer_wbl2 sc1
	s_waitcnt vmcnt(0)
	s_waitcnt vmcnt(0)
	v_cmp_eq_u32_e32 vcc, 0, v0
	s_and_saveexec_b64 s[2:3], vcc
	s_cbranch_execz .LBB0_597
	s_sub_i32 s4, 13, s34
	s_and_b32 s5, s12, 7
	s_sub_i32 s6, s13, s5
	s_add_i32 s6, s6, 7
	s_lshr_b32 s6, s6, 3
	s_mul_i32 s6, s6, s4
	s_lshl_b32 s5, s5, 8
	v_mov_b32_e32 v0, s5
	v_mov_b32_e32 v1, 1
	global_atomic_add v1, v0, v1, s[68:69] sc0
	s_min_u32 s7, s13, 8
	s_mul_i32 s7, s7, s4
	s_waitcnt vmcnt(0)
	v_add_u32_e32 v1, 1, v1
	v_cmp_eq_u32_e32 vcc, s6, v1
	s_cbranch_vccz .Lgb_wait_s12
	v_mov_b32_e32 v0, 0x1000
	v_mov_b32_e32 v1, 1
	global_atomic_add v1, v0, v1, s[68:69] sc0
	s_waitcnt vmcnt(0)
	v_add_u32_e32 v1, 1, v1
	v_cmp_eq_u32_e32 vcc, s7, v1
	s_cbranch_vccz .Lgb_wait_s12
	v_mov_b32_e32 v0, 0
	v_mov_b32_e32 v1, 1
	global_atomic_add v0, v1, s[14:15]

.LBB0_624:
	s_cmp_lt_i32 s35, 15
	s_cbranch_scc1 .LBB0_633
	v_mbcnt_lo_u32_b32 v0, -1, 0
	v_mbcnt_hi_u32_b32 v0, -1, v0
	s_waitcnt vmcnt(0) lgkmcnt(0)
	s_waitcnt vmcnt(0) lgkmcnt(0)
	v_add_u32_e32 v0, s84, v0
	v_cmp_gt_u32_e32 vcc, 64, v0
	s_barrier
	s_and_saveexec_b64 s[0:1], vcc
	s_cbranch_execz .LBB0_632
	buffer_wbl2 sc1
	s_waitcnt vmcnt(0)
	v_cmp_eq_u32_e32 vcc, 0, v0
	s_and_saveexec_b64 s[2:3], vcc
	s_cbranch_execz .LBB0_631
	s_sub_i32 s4, 14, s34
	s_and_b32 s5, s12, 7
	s_sub_i32 s6, s13, s5
	s_add_i32 s6, s6, 7
	s_lshr_b32 s6, s6, 3
	s_mul_i32 s6, s6, s4
	s_lshl_b32 s5, s5, 8
	v_mov_b32_e32 v0, s5
	v_mov_b32_e32 v1, 1
	global_atomic_add v1, v0, v1, s[68:69] sc0
	s_min_u32 s7, s13, 8
	s_mul_i32 s7, s7, s4
	s_waitcnt vmcnt(0)
	v_add_u32_e32 v1, 1, v1
	v_cmp_eq_u32_e32 vcc, s6, v1
	s_cbranch_vccz .Lgb_wait_s13
	v_mov_b32_e32 v0, 0x1000
	v_mov_b32_e32 v1, 1
	global_atomic_add v1, v0, v1, s[68:69] sc0
	s_waitcnt vmcnt(0)
	v_add_u32_e32 v1, 1, v1
	v_cmp_eq_u32_e32 vcc, s7, v1
	s_cbranch_vccz .Lgb_wait_s13
	v_mov_b32_e32 v0, 0
	v_mov_b32_e32 v1, 1
	global_atomic_add v0, v1, s[14:15]

.Lmla_ret14:
.LBB0_668:
	s_cmp_lt_i32 s35, 16
	s_cbranch_scc1 .LBB0_677
	v_mbcnt_lo_u32_b32 v0, -1, 0
	v_mbcnt_hi_u32_b32 v0, -1, v0
	s_waitcnt vmcnt(0) lgkmcnt(0)
	s_waitcnt lgkmcnt(0)
	v_add_u32_e32 v0, s84, v0
	v_cmp_gt_u32_e32 vcc, 64, v0
	s_barrier
	s_and_saveexec_b64 s[0:1], vcc
	s_cbranch_execz .LBB0_676
	buffer_wbl2 sc1
	s_waitcnt vmcnt(0)
	s_waitcnt vmcnt(0)
	v_cmp_eq_u32_e32 vcc, 0, v0
	s_and_saveexec_b64 s[2:3], vcc
	s_cbranch_execz .LBB0_675
	s_sub_i32 s4, 15, s34
	s_and_b32 s5, s12, 7
	s_sub_i32 s6, s13, s5
	s_add_i32 s6, s6, 7
	s_lshr_b32 s6, s6, 3
	s_mul_i32 s6, s6, s4
	s_lshl_b32 s5, s5, 8
	v_mov_b32_e32 v0, s5
	v_mov_b32_e32 v1, 1
	global_atomic_add v1, v0, v1, s[68:69] sc0
	s_min_u32 s7, s13, 8
	s_mul_i32 s7, s7, s4
	s_waitcnt vmcnt(0)
	v_add_u32_e32 v1, 1, v1
	v_cmp_eq_u32_e32 vcc, s6, v1
	s_cbranch_vccz .Lgb_wait_s14
	v_mov_b32_e32 v0, 0x1000
	v_mov_b32_e32 v1, 1
	global_atomic_add v1, v0, v1, s[68:69] sc0
	s_waitcnt vmcnt(0)
	v_add_u32_e32 v1, 1, v1
	v_cmp_eq_u32_e32 vcc, s7, v1
	s_cbranch_vccz .Lgb_wait_s14
	v_mov_b32_e32 v0, 0
	v_mov_b32_e32 v1, 1
	global_atomic_add v0, v1, s[14:15]

.LBB0_681:
	s_or_b64 exec, exec, s[2:3]
	s_cmp_lt_u32 s35, 17
	s_cbranch_scc1 .LBB0_690
	v_mbcnt_lo_u32_b32 v0, -1, 0
	v_mbcnt_hi_u32_b32 v0, -1, v0
	s_waitcnt vmcnt(0) lgkmcnt(0)
	s_waitcnt lgkmcnt(0)
	v_add_u32_e32 v0, s84, v0
	v_cmp_gt_u32_e32 vcc, 64, v0
	s_barrier
	s_and_saveexec_b64 s[0:1], vcc
	s_cbranch_execz .LBB0_689
	buffer_wbl2 sc1
	s_waitcnt vmcnt(0)
	s_waitcnt vmcnt(0)
	v_cmp_eq_u32_e32 vcc, 0, v0
	s_and_saveexec_b64 s[2:3], vcc
	s_cbranch_execz .LBB0_688
	s_sub_i32 s4, 16, s34
	s_and_b32 s5, s12, 7
	s_sub_i32 s6, s13, s5
	s_add_i32 s6, s6, 7
	s_lshr_b32 s6, s6, 3
	s_mul_i32 s6, s6, s4
	s_lshl_b32 s5, s5, 8
	v_mov_b32_e32 v0, s5
	v_mov_b32_e32 v1, 1
	global_atomic_add v1, v0, v1, s[68:69] sc0
	s_min_u32 s7, s13, 8
	s_mul_i32 s7, s7, s4
	s_waitcnt vmcnt(0)
	v_add_u32_e32 v1, 1, v1
	v_cmp_eq_u32_e32 vcc, s6, v1
	s_cbranch_vccz .Lgb_wait_s15
	v_mov_b32_e32 v0, 0x1000
	v_mov_b32_e32 v1, 1
	global_atomic_add v1, v0, v1, s[68:69] sc0
	s_waitcnt vmcnt(0)
	v_add_u32_e32 v1, 1, v1
	v_cmp_eq_u32_e32 vcc, s7, v1
	s_cbranch_vccz .Lgb_wait_s15
	v_mov_b32_e32 v0, 0
	v_mov_b32_e32 v1, 1
	global_atomic_add v0, v1, s[14:15]

.LBB0_706:
	s_cmp_lt_i32 s35, 18
	s_cbranch_scc1 .LBB0_715
	v_mbcnt_lo_u32_b32 v0, -1, 0
	v_mbcnt_hi_u32_b32 v0, -1, v0
	s_waitcnt vmcnt(0) lgkmcnt(0)
	s_waitcnt vmcnt(0) lgkmcnt(0)
	v_add_u32_e32 v0, s84, v0
	v_cmp_gt_u32_e32 vcc, 64, v0
	s_barrier
	s_and_saveexec_b64 s[0:1], vcc
	s_cbranch_execz .LBB0_714
	buffer_wbl2 sc1
	s_waitcnt vmcnt(0)
	v_cmp_eq_u32_e32 vcc, 0, v0
	s_and_saveexec_b64 s[2:3], vcc
	s_cbranch_execz .LBB0_713
	s_sub_i32 s4, 17, s34
	s_and_b32 s5, s12, 7
	s_sub_i32 s6, s13, s5
	s_add_i32 s6, s6, 7
	s_lshr_b32 s6, s6, 3
	s_mul_i32 s6, s6, s4
	s_lshl_b32 s5, s5, 8
	v_mov_b32_e32 v0, s5
	v_mov_b32_e32 v1, 1
	global_atomic_add v1, v0, v1, s[68:69] sc0
	s_min_u32 s7, s13, 8
	s_mul_i32 s7, s7, s4
	s_waitcnt vmcnt(0)
	v_add_u32_e32 v1, 1, v1
	v_cmp_eq_u32_e32 vcc, s6, v1
	s_cbranch_vccz .Lgb_wait_s16
	v_mov_b32_e32 v0, 0x1000
	v_mov_b32_e32 v1, 1
	global_atomic_add v1, v0, v1, s[68:69] sc0
	s_waitcnt vmcnt(0)
	v_add_u32_e32 v1, 1, v1
	v_cmp_eq_u32_e32 vcc, s7, v1
	s_cbranch_vccz .Lgb_wait_s16
	v_mov_b32_e32 v0, 0
	v_mov_b32_e32 v1, 1
	global_atomic_add v0, v1, s[14:15]

.LBB0_719:
	s_or_b64 exec, exec, s[0:1]
	s_cmp_lt_u32 s35, 19
	s_cbranch_scc1 .LBB0_728
	v_mbcnt_lo_u32_b32 v0, -1, 0
	v_mbcnt_hi_u32_b32 v0, -1, v0
	s_waitcnt vmcnt(0) lgkmcnt(0)
	s_nop 0
	v_add_u32_e32 v0, s84, v0
	v_cmp_gt_u32_e32 vcc, 64, v0
	s_barrier
	s_and_saveexec_b64 s[0:1], vcc
	s_cbranch_execz .LBB0_727
	buffer_wbl2 sc1
	s_waitcnt vmcnt(0)
	s_waitcnt vmcnt(0)
	v_cmp_eq_u32_e32 vcc, 0, v0
	s_and_saveexec_b64 s[2:3], vcc
	s_cbranch_execz .LBB0_726
	s_sub_i32 s4, 18, s34
	s_and_b32 s5, s12, 7
	s_sub_i32 s6, s13, s5
	s_add_i32 s6, s6, 7
	s_lshr_b32 s6, s6, 3
	s_mul_i32 s6, s6, s4
	s_lshl_b32 s5, s5, 8
	v_mov_b32_e32 v0, s5
	v_mov_b32_e32 v1, 1
	global_atomic_add v1, v0, v1, s[68:69] sc0
	s_min_u32 s7, s13, 8
	s_mul_i32 s7, s7, s4
	s_waitcnt vmcnt(0)
	v_add_u32_e32 v1, 1, v1
	v_cmp_eq_u32_e32 vcc, s6, v1
	s_cbranch_vccz .Lgb_wait_s17
	v_mov_b32_e32 v0, 0x1000
	v_mov_b32_e32 v1, 1
	global_atomic_add v1, v0, v1, s[68:69] sc0
	s_waitcnt vmcnt(0)
	v_add_u32_e32 v1, 1, v1
	v_cmp_eq_u32_e32 vcc, s7, v1
	s_cbranch_vccz .Lgb_wait_s17
	v_mov_b32_e32 v0, 0
	v_mov_b32_e32 v1, 1
	global_atomic_add v0, v1, s[14:15]

.LBB0_744:
	s_cmp_lt_i32 s35, 20
	s_cbranch_scc1 .LBB0_753
	v_mbcnt_lo_u32_b32 v0, -1, 0
	v_mbcnt_hi_u32_b32 v0, -1, v0
	s_waitcnt vmcnt(0) lgkmcnt(0)
	s_waitcnt vmcnt(0) lgkmcnt(0)
	v_add_u32_e32 v0, s84, v0
	v_cmp_gt_u32_e32 vcc, 64, v0
	s_barrier
	s_and_saveexec_b64 s[0:1], vcc
	s_cbranch_execz .LBB0_752
	buffer_wbl2 sc1
	s_waitcnt vmcnt(0)
	v_cmp_eq_u32_e32 vcc, 0, v0
	s_and_saveexec_b64 s[2:3], vcc
	s_cbranch_execz .LBB0_751
	s_sub_i32 s4, 19, s34
	s_and_b32 s5, s12, 7
	s_sub_i32 s6, s13, s5
	s_add_i32 s6, s6, 7
	s_lshr_b32 s6, s6, 3
	s_mul_i32 s6, s6, s4
	s_lshl_b32 s5, s5, 8
	v_mov_b32_e32 v0, s5
	v_mov_b32_e32 v1, 1
	global_atomic_add v1, v0, v1, s[68:69] sc0
	s_min_u32 s7, s13, 8
	s_mul_i32 s7, s7, s4
	s_waitcnt vmcnt(0)
	v_add_u32_e32 v1, 1, v1
	v_cmp_eq_u32_e32 vcc, s6, v1
	s_cbranch_vccz .Lgb_wait_s18
	v_mov_b32_e32 v0, 0x1000
	v_mov_b32_e32 v1, 1
	global_atomic_add v1, v0, v1, s[68:69] sc0
	s_waitcnt vmcnt(0)
	v_add_u32_e32 v1, 1, v1
	v_cmp_eq_u32_e32 vcc, s7, v1
	s_cbranch_vccz .Lgb_wait_s18
	v_mov_b32_e32 v0, 0
	v_mov_b32_e32 v1, 1
	global_atomic_add v0, v1, s[14:15]

.LBB0_769:
	s_cmp_lt_i32 s35, 21
	s_cbranch_scc1 .LBB0_778
	v_mbcnt_lo_u32_b32 v0, -1, 0
	v_mbcnt_hi_u32_b32 v0, -1, v0
	s_waitcnt vmcnt(0) lgkmcnt(0)
	s_waitcnt vmcnt(0) lgkmcnt(0)
	v_add_u32_e32 v0, s84, v0
	v_cmp_gt_u32_e32 vcc, 64, v0
	s_barrier
	s_and_saveexec_b64 s[0:1], vcc
	s_cbranch_execz .LBB0_777
	buffer_wbl2 sc1
	s_waitcnt vmcnt(0)
	v_cmp_eq_u32_e32 vcc, 0, v0
	s_and_saveexec_b64 s[2:3], vcc
	s_cbranch_execz .LBB0_776
	s_sub_i32 s4, 20, s34
	s_and_b32 s5, s12, 7
	s_sub_i32 s6, s13, s5
	s_add_i32 s6, s6, 7
	s_lshr_b32 s6, s6, 3
	s_mul_i32 s6, s6, s4
	s_lshl_b32 s5, s5, 8
	v_mov_b32_e32 v0, s5
	v_mov_b32_e32 v1, 1
	global_atomic_add v1, v0, v1, s[68:69] sc0
	s_min_u32 s7, s13, 8
	s_mul_i32 s7, s7, s4
	s_waitcnt vmcnt(0)
	v_add_u32_e32 v1, 1, v1
	v_cmp_eq_u32_e32 vcc, s6, v1
	s_cbranch_vccz .Lgb_wait_s19
	v_mov_b32_e32 v0, 0x1000
	v_mov_b32_e32 v1, 1
	global_atomic_add v1, v0, v1, s[68:69] sc0
	s_waitcnt vmcnt(0)
	v_add_u32_e32 v1, 1, v1
	v_cmp_eq_u32_e32 vcc, s7, v1
	s_cbranch_vccz .Lgb_wait_s19
	v_mov_b32_e32 v0, 0
	v_mov_b32_e32 v1, 1
	global_atomic_add v0, v1, s[14:15]

.LBB0_782:
	s_or_b64 exec, exec, s[0:1]
	s_cmp_lt_u32 s35, 22
	s_cbranch_scc1 .LBB0_791
	v_mbcnt_lo_u32_b32 v0, -1, 0
	v_mbcnt_hi_u32_b32 v0, -1, v0
	s_waitcnt vmcnt(0) lgkmcnt(0)
	s_waitcnt lgkmcnt(0)
	v_add_u32_e32 v0, s84, v0
	v_cmp_gt_u32_e32 vcc, 64, v0
	s_barrier
	s_and_saveexec_b64 s[0:1], vcc
	s_cbranch_execz .LBB0_790
	buffer_wbl2 sc1
	s_waitcnt vmcnt(0)
	s_waitcnt vmcnt(0)
	v_cmp_eq_u32_e32 vcc, 0, v0
	s_and_saveexec_b64 s[2:3], vcc
	s_cbranch_execz .LBB0_789
	s_sub_i32 s4, 21, s34
	s_and_b32 s5, s12, 7
	s_sub_i32 s6, s13, s5
	s_add_i32 s6, s6, 7
	s_lshr_b32 s6, s6, 3
	s_mul_i32 s6, s6, s4
	s_lshl_b32 s5, s5, 8
	v_mov_b32_e32 v0, s5
	v_mov_b32_e32 v1, 1
	global_atomic_add v1, v0, v1, s[68:69] sc0
	s_min_u32 s7, s13, 8
	s_mul_i32 s7, s7, s4
	s_waitcnt vmcnt(0)
	v_add_u32_e32 v1, 1, v1
	v_cmp_eq_u32_e32 vcc, s6, v1
	s_cbranch_vccz .Lgb_wait_s20
	v_mov_b32_e32 v0, 0x1000
	v_mov_b32_e32 v1, 1
	global_atomic_add v1, v0, v1, s[68:69] sc0
	s_waitcnt vmcnt(0)
	v_add_u32_e32 v1, 1, v1
	v_cmp_eq_u32_e32 vcc, s7, v1
	s_cbranch_vccz .Lgb_wait_s20
	v_mov_b32_e32 v0, 0
	v_mov_b32_e32 v1, 1
	global_atomic_add v0, v1, s[14:15]
